# v15: v12 + redundant final grid barrier (after the last LayerNorm) removed
# baseline (speedup 1.0000x reference)
.LBB0_3809:
	s_or_b64 exec, exec, s[0:1]
	s_endpgm
